# FOXIN: half of the workgroups (bid bit 3) start the phase ~5us late to desynchronize epilogue store bursts
# speedup vs baseline: 1.0051x; 1.0005x over previous
.LBB0_123:
	s_cmp_lt_i32 s30, 2
	s_cselect_b64 s[8:9], -1, 0
	s_add_u32 s2, s28, 0x4a0000
	s_addc_u32 s3, s29, 0
	v_writelane_b32 v254, s2, 14
	s_and_b64 s[0:1], s[8:9], s[0:1]
	s_andn2_b64 vcc, exec, s[0:1]
	v_writelane_b32 v254, s3, 15
	v_writelane_b32 v254, s97, 16
	s_cbranch_vccnz .LBB0_295
	s_and_b32 s98, s16, 8
	s_cmp_eq_u32 s98, 0
	s_cbranch_scc1 .Lstg_foxin_done
	s_sleep 127
	s_sleep 60
.Lstg_foxin_done:
	v_mbcnt_lo_u32_b32 v26, -1, 0
	v_mbcnt_hi_u32_b32 v26, -1, v26
	s_cmpk_lt_i32 s16, 0x400
	v_add_u32_e32 v0, s33, v26
	s_cselect_b64 s[4:5], -1, 0
	s_cmpk_gt_i32 s16, 0x3ff
	v_readfirstlane_b32 s10, v0
	s_cbranch_scc1 .LBB0_127
	s_ashr_i32 s0, s16, 31
	s_lshr_b32 s0, s0, 29
	s_add_i32 s2, s16, s0
	s_and_b32 s0, s2, -8
	s_sub_i32 s3, s16, s0
	s_cmp_gt_i32 s3, -1
	s_cbranch_scc0 .LBB0_128
	s_lshl_b32 s6, s3, 7
	s_cbranch_execz .LBB0_129
	s_branch .LBB0_130

	.amdhsa_kernel _Z6mk_fwd4Args
		.amdhsa_group_segment_fixed_size 0
		.amdhsa_private_segment_fixed_size 0
		.amdhsa_kernarg_size 440
		.amdhsa_user_sgpr_count 2
		.amdhsa_user_sgpr_dispatch_ptr 0
		.amdhsa_user_sgpr_queue_ptr 0
		.amdhsa_user_sgpr_kernarg_segment_ptr 1
		.amdhsa_user_sgpr_dispatch_id 0
		.amdhsa_user_sgpr_kernarg_preload_length 0
		.amdhsa_user_sgpr_kernarg_preload_offset 0
		.amdhsa_user_sgpr_private_segment_size 0
		.amdhsa_uses_dynamic_stack 0
		.amdhsa_enable_private_segment 0
		.amdhsa_system_sgpr_workgroup_id_x 1
		.amdhsa_system_sgpr_workgroup_id_y 0
		.amdhsa_system_sgpr_workgroup_id_z 0
		.amdhsa_system_sgpr_workgroup_info 0
		.amdhsa_system_vgpr_workitem_id 0
		.amdhsa_next_free_vgpr 255
		.amdhsa_next_free_sgpr 102
		.amdhsa_accum_offset 256
		.amdhsa_reserve_vcc 1
		.amdhsa_float_round_mode_32 0
		.amdhsa_float_round_mode_16_64 0
		.amdhsa_float_denorm_mode_32 3
		.amdhsa_float_denorm_mode_16_64 3
		.amdhsa_dx10_clamp 1
		.amdhsa_ieee_mode 1
		.amdhsa_fp16_overflow 0
		.amdhsa_tg_split 0
		.amdhsa_exception_fp_ieee_invalid_op 0
		.amdhsa_exception_fp_denorm_src 0
		.amdhsa_exception_fp_ieee_div_zero 0
		.amdhsa_exception_fp_ieee_overflow 0
		.amdhsa_exception_fp_ieee_underflow 0
		.amdhsa_exception_fp_ieee_inexact 0
		.amdhsa_exception_int_div_zero 0
	.end_amdhsa_kernel

amdhsa.kernels:
  - .agpr_count:     0
    .args:
      - .offset:         0
        .size:           184
        .value_kind:     by_value
      - .offset:         184
        .size:           4
        .value_kind:     hidden_block_count_x
      - .offset:         188
        .size:           4
        .value_kind:     hidden_block_count_y
      - .offset:         192
        .size:           4
        .value_kind:     hidden_block_count_z
      - .offset:         196
        .size:           2
        .value_kind:     hidden_group_size_x
      - .offset:         198
        .size:           2
        .value_kind:     hidden_group_size_y
      - .offset:         200
        .size:           2
        .value_kind:     hidden_group_size_z
      - .offset:         202
        .size:           2
        .value_kind:     hidden_remainder_x
      - .offset:         204
        .size:           2
        .value_kind:     hidden_remainder_y
      - .offset:         206
        .size:           2
        .value_kind:     hidden_remainder_z
      - .offset:         224
        .size:           8
        .value_kind:     hidden_global_offset_x
      - .offset:         232
        .size:           8
        .value_kind:     hidden_global_offset_y
      - .offset:         240
        .size:           8
        .value_kind:     hidden_global_offset_z
      - .offset:         248
        .size:           2
        .value_kind:     hidden_grid_dims
      - .offset:         304
        .size:           4
        .value_kind:     hidden_dynamic_lds_size
    .group_segment_fixed_size: 0
    .kernarg_segment_align: 8
    .kernarg_segment_size: 440
    .language:       OpenCL C
    .language_version:
      - 2
      - 0
    .max_flat_workgroup_size: 512
    .name:           _Z6mk_fwd4Args
    .private_segment_fixed_size: 0
    .sgpr_count:     108
    .sgpr_spill_count: 43
    .symbol:         _Z6mk_fwd4Args.kd
    .uniform_work_group_size: 1
    .uses_dynamic_stack: false
    .vgpr_count:     255
    .vgpr_spill_count: 0
    .wavefront_size: 64
